# phase1 rmsnorm row-sum butterfly via permlane32/16_swap + DPP adds instead of 6 serial ds_bpermute hops
# baseline (speedup 1.0000x reference)
; __device__ __forceinline__ unsigned pk2(float lo, float hi) { unsigned r; asm("v_cvt_pk_bf16_f32 %0, %1, %2" : "=v"(r) : "v"(lo), "v"(hi)); return r; }
; __device__ __forceinline__ float row_rstd(const f32x4 (&v)[4]) {
;     float ss = 0.f;
; #pragma unroll
;     for (int j = 0; j < 4; ++j) ss += v[j][0] * v[j][0] + v[j][1] * v[j][1] + v[j][2] * v[j][2] + v[j][3] * v[j][3];
;     return rsqrtf(wave_sum(ss) * (1.0f / D) + EPS);
; __device__ __forceinline__ void phase1(PP p, int wv) {
;     ...
;                 const float rstd = row_rstd(v[q]);
; #pragma unroll
;                 for (int j = 0; j < 4; ++j) {
;                     const f32x4 o = v[q][j] * rstd * gsc[j] + gsh[j];
;                     u32x2 w; w.x = pk2(o[0], o[1]); w.y = pk2(o[2], o[3]);
;                     *(u32x2*)(hb + (size_t)r * D + 4 * lane + 256 * j) = w;
;                 }
.LBB0_130:
	s_or_b64 exec, exec, s[6:7]
	v_mov_b32_e32 v52, v17
	v_mov_b32_e32 v53, v9
	v_mov_b32_e32 v50, v16
	v_mov_b32_e32 v51, v8
	v_pk_mul_f32 v[52:53], v[52:53], v[52:53]
	v_mov_b32_e32 v54, v5
	v_pk_fma_f32 v[50:51], v[50:51], v[50:51], v[52:53]
	v_mov_b32_e32 v52, v18
	v_mov_b32_e32 v53, v10
	v_pk_fma_f32 v[50:51], v[52:53], v[52:53], v[50:51]
	v_mov_b32_e32 v52, v19
	v_mov_b32_e32 v53, v11
	v_mov_b32_e32 v55, v1
	v_pk_fma_f32 v[50:51], v[52:53], v[52:53], v[50:51]
	v_mov_b32_e32 v52, v4
	v_mov_b32_e32 v53, v0
	v_pk_mul_f32 v[54:55], v[54:55], v[54:55]
	v_add_f32_e32 v49, v50, v51
	v_pk_fma_f32 v[52:53], v[52:53], v[52:53], v[54:55]
	v_mov_b32_e32 v54, v6
	v_mov_b32_e32 v55, v2
	v_pk_fma_f32 v[52:53], v[54:55], v[54:55], v[52:53]
	v_mov_b32_e32 v54, v7
	v_mov_b32_e32 v55, v3
	v_pk_fma_f32 v[52:53], v[54:55], v[54:55], v[52:53]
	s_nop 0
	v_add_f32_e32 v49, v49, v52
	v_add_f32_e32 v49, v49, v53
	v_mov_b32_e32 v50, v49
	s_nop 1
	v_permlane32_swap_b32_e32 v49, v50
	v_add_f32_e32 v49, v49, v50
	v_mov_b32_e32 v50, v49
	s_nop 1
	v_permlane16_swap_b32_e32 v49, v50
	v_add_f32_e32 v49, v49, v50
	s_nop 1
	v_add_f32_dpp v49, v49, v49 row_ror:8 row_mask:0xf bank_mask:0xf
	s_nop 1
	v_add_f32_dpp v49, v49, v49 row_ror:4 row_mask:0xf bank_mask:0xf
	s_nop 1
	v_add_f32_dpp v49, v49, v49 quad_perm:[2,3,0,1] row_mask:0xf bank_mask:0xf
	s_nop 1
	v_add_f32_dpp v49, v49, v49 quad_perm:[1,0,3,2] row_mask:0xf bank_mask:0xf
	v_fmamk_f32 v49, v49, 0x3a800000, v123
	v_mul_f32_e32 v50, 0x4b800000, v49
	v_cmp_gt_f32_e32 vcc, s41, v49
	s_nop 1
	v_cndmask_b32_e32 v49, v49, v50, vcc
	v_rsq_f32_e32 v50, v49
	v_ashrrev_i32_e32 v49, 31, v48
	v_lshlrev_b64 v[48:49], 11, v[48:49]
	v_lshl_add_u64 v[48:49], v[100:101], 0, v[48:49]
	v_mul_f32_e32 v51, 0x45800000, v50
	v_cndmask_b32_e32 v50, v50, v51, vcc
	v_pk_mul_f32 v[16:17], v[16:17], v[50:51] op_sel_hi:[1,0]
	v_pk_mul_f32 v[8:9], v[8:9], v[50:51] op_sel_hi:[1,0]
	v_pk_mul_f32 v[4:5], v[4:5], v[50:51] op_sel_hi:[1,0]
	v_pk_mul_f32 v[0:1], v[0:1], v[50:51] op_sel_hi:[1,0]
	v_pk_mul_f32 v[18:19], v[18:19], v[50:51] op_sel_hi:[1,0]
	v_pk_fma_f32 v[16:17], v[28:29], v[16:17], v[12:13]
	v_pk_mul_f32 v[10:11], v[10:11], v[50:51] op_sel_hi:[1,0]
	s_waitcnt vmcnt(2)
	v_pk_fma_f32 v[8:9], v[32:33], v[8:9], v[20:21]
	v_pk_mul_f32 v[6:7], v[6:7], v[50:51] op_sel_hi:[1,0]
	s_waitcnt vmcnt(1)
	v_pk_fma_f32 v[4:5], v[36:37], v[4:5], v[24:25]
	v_pk_mul_f32 v[2:3], v[2:3], v[50:51] op_sel_hi:[1,0]
	s_waitcnt vmcnt(0)
	v_pk_fma_f32 v[0:1], v[44:45], v[0:1], v[40:41]
	v_pk_fma_f32 v[18:19], v[30:31], v[18:19], v[14:15]
	v_cvt_pk_bf16_f32 v16, v16, v17
	v_pk_fma_f32 v[10:11], v[34:35], v[10:11], v[22:23]
	v_cvt_pk_bf16_f32 v17, v18, v19
	global_store_dwordx2 v[48:49], v[16:17], off
	v_cvt_pk_bf16_f32 v8, v8, v9
	v_cvt_pk_bf16_f32 v9, v10, v11
	global_store_dwordx2 v[48:49], v[8:9], off offset:512
	v_pk_fma_f32 v[6:7], v[38:39], v[6:7], v[26:27]
	v_cvt_pk_bf16_f32 v4, v4, v5
	v_pk_fma_f32 v[2:3], v[46:47], v[2:3], v[42:43]
	v_cvt_pk_bf16_f32 v5, v6, v7
	global_store_dwordx2 v[48:49], v[4:5], off offset:1024
	v_cvt_pk_bf16_f32 v0, v0, v1
	v_cvt_pk_bf16_f32 v1, v2, v3
	global_store_dwordx2 v[48:49], v[0:1], off offset:1536

; __device__ __forceinline__ unsigned pk2(float lo, float hi) { unsigned r; asm("v_cvt_pk_bf16_f32 %0, %1, %2" : "=v"(r) : "v"(lo), "v"(hi)); return r; }
; __device__ __forceinline__ float row_rstd(const f32x4 (&v)[4]) {
;     float ss = 0.f;
; #pragma unroll
;     for (int j = 0; j < 4; ++j) ss += v[j][0] * v[j][0] + v[j][1] * v[j][1] + v[j][2] * v[j][2] + v[j][3] * v[j][3];
;     return rsqrtf(wave_sum(ss) * (1.0f / D) + EPS);
; __device__ __forceinline__ void phase1(PP p, int wv) {
;     ...
;                 const float rstd = row_rstd(v[q]);
; #pragma unroll
;                 for (int j = 0; j < 4; ++j) {
;                     const f32x4 o = v[q][j] * rstd * gsc[j] + gsh[j];
;                     u32x2 w; w.x = pk2(o[0], o[1]); w.y = pk2(o[2], o[3]);
;                     *(u32x2*)(hb + (size_t)r * D + 4 * lane + 256 * j) = w;
;                 }
.LBB0_134:
	s_or_b64 exec, exec, s[10:11]
	s_waitcnt vmcnt(15)
	v_mov_b32_e32 v126, v93
	s_waitcnt vmcnt(14)
	v_mov_b32_e32 v127, v89
	v_mov_b32_e32 v124, v92
	v_mov_b32_e32 v125, v88
	v_pk_mul_f32 v[126:127], v[126:127], v[126:127]
	s_waitcnt vmcnt(13)
	v_mov_b32_e32 v128, v85
	v_pk_fma_f32 v[124:125], v[124:125], v[124:125], v[126:127]
	v_mov_b32_e32 v126, v94
	v_mov_b32_e32 v127, v90
	v_pk_fma_f32 v[124:125], v[126:127], v[126:127], v[124:125]
	v_mov_b32_e32 v126, v95
	v_mov_b32_e32 v127, v91
	s_waitcnt vmcnt(12)
	v_mov_b32_e32 v129, v81
	v_pk_fma_f32 v[124:125], v[126:127], v[126:127], v[124:125]
	v_mov_b32_e32 v126, v84
	v_mov_b32_e32 v127, v80
	v_pk_mul_f32 v[128:129], v[128:129], v[128:129]
	v_add_f32_e32 v98, v124, v125
	v_pk_fma_f32 v[126:127], v[126:127], v[126:127], v[128:129]
	v_mov_b32_e32 v128, v86
	v_mov_b32_e32 v129, v82
	v_pk_fma_f32 v[126:127], v[128:129], v[128:129], v[126:127]
	v_mov_b32_e32 v128, v87
	v_mov_b32_e32 v129, v83
	v_pk_fma_f32 v[126:127], v[128:129], v[128:129], v[126:127]
	v_lshl_add_u64 v[124:125], v[110:111], 0, v[108:109]
	v_add_f32_e32 v98, v98, v126
	v_add_f32_e32 v98, v98, v127
	v_mov_b32_e32 v119, v98
	s_nop 1
	v_permlane32_swap_b32_e32 v98, v119
	v_add_f32_e32 v98, v98, v119
	v_mov_b32_e32 v119, v98
	s_nop 1
	v_permlane16_swap_b32_e32 v98, v119
	v_add_f32_e32 v98, v98, v119
	s_nop 1
	v_add_f32_dpp v98, v98, v98 row_ror:8 row_mask:0xf bank_mask:0xf
	s_nop 1
	v_add_f32_dpp v98, v98, v98 row_ror:4 row_mask:0xf bank_mask:0xf
	s_nop 1
	v_add_f32_dpp v98, v98, v98 quad_perm:[2,3,0,1] row_mask:0xf bank_mask:0xf
	s_nop 1
	v_add_f32_dpp v98, v98, v98 quad_perm:[1,0,3,2] row_mask:0xf bank_mask:0xf
	v_fmamk_f32 v98, v98, 0x3a800000, v123
	v_mul_f32_e32 v119, 0x4b800000, v98
	v_cmp_gt_f32_e64 s[8:9], s41, v98
	s_nop 1
	v_cndmask_b32_e64 v98, v98, v119, s[8:9]
	v_rsq_f32_e32 v98, v98
	s_nop 0
	v_mul_f32_e32 v119, 0x45800000, v98
	v_cndmask_b32_e64 v98, v98, v119, s[8:9]
	v_pk_mul_f32 v[92:93], v[92:93], v[98:99] op_sel_hi:[1,0]
	v_pk_mul_f32 v[94:95], v[94:95], v[98:99] op_sel_hi:[1,0]
	v_pk_fma_f32 v[92:93], v[28:29], v[92:93], v[12:13]
	v_pk_fma_f32 v[94:95], v[30:31], v[94:95], v[14:15]
	v_cvt_pk_bf16_f32 v92, v92, v93
	v_pk_mul_f32 v[88:89], v[88:89], v[98:99] op_sel_hi:[1,0]
	v_cvt_pk_bf16_f32 v93, v94, v95
	v_add_co_u32_e64 v94, s[8:9], s42, v124
	v_pk_mul_f32 v[84:85], v[84:85], v[98:99] op_sel_hi:[1,0]
	v_pk_mul_f32 v[80:81], v[80:81], v[98:99] op_sel_hi:[1,0]
	v_addc_co_u32_e64 v95, s[8:9], 0, v125, s[8:9]
	v_pk_mul_f32 v[90:91], v[90:91], v[98:99] op_sel_hi:[1,0]
	v_pk_fma_f32 v[88:89], v[32:33], v[88:89], v[20:21]
	v_pk_mul_f32 v[86:87], v[86:87], v[98:99] op_sel_hi:[1,0]
	v_pk_fma_f32 v[84:85], v[36:37], v[84:85], v[24:25]
	v_pk_mul_f32 v[82:83], v[82:83], v[98:99] op_sel_hi:[1,0]
	s_waitcnt vmcnt(0)
	v_pk_fma_f32 v[80:81], v[44:45], v[80:81], v[40:41]
	global_store_dwordx2 v[94:95], v[92:93], off
	v_pk_fma_f32 v[90:91], v[34:35], v[90:91], v[22:23]
	v_cvt_pk_bf16_f32 v88, v88, v89
	v_pk_fma_f32 v[86:87], v[38:39], v[86:87], v[26:27]
	v_cvt_pk_bf16_f32 v89, v90, v91
	global_store_dwordx2 v[94:95], v[88:89], off offset:512
	v_cvt_pk_bf16_f32 v84, v84, v85
	v_cvt_pk_bf16_f32 v85, v86, v87
	global_store_dwordx2 v[94:95], v[84:85], off offset:1024
	v_pk_fma_f32 v[82:83], v[46:47], v[82:83], v[42:43]
	v_cvt_pk_bf16_f32 v80, v80, v81
	s_nop 0
	v_cvt_pk_bf16_f32 v81, v82, v83
	global_store_dwordx2 v[94:95], v[80:81], off offset:1536
	s_and_saveexec_b64 s[8:9], s[4:5]
	s_cbranch_execnz .LBB0_137
	s_or_b64 exec, exec, s[8:9]
	s_and_saveexec_b64 s[8:9], s[6:7]
	s_cbranch_execnz .LBB0_140

; __device__ __forceinline__ unsigned pk2(float lo, float hi) { unsigned r; asm("v_cvt_pk_bf16_f32 %0, %1, %2" : "=v"(r) : "v"(lo), "v"(hi)); return r; }
; __device__ __forceinline__ float row_rstd(const f32x4 (&v)[4]) {
;     float ss = 0.f;
; #pragma unroll
;     for (int j = 0; j < 4; ++j) ss += v[j][0] * v[j][0] + v[j][1] * v[j][1] + v[j][2] * v[j][2] + v[j][3] * v[j][3];
;     return rsqrtf(wave_sum(ss) * (1.0f / D) + EPS);
; __device__ __forceinline__ void phase1(PP p, int wv) {
;     ...
;                 const float rstd = row_rstd(v[q]);
; #pragma unroll
;                 for (int j = 0; j < 4; ++j) {
;                     const f32x4 o = v[q][j] * rstd * gsc[j] + gsh[j];
;                     u32x2 w; w.x = pk2(o[0], o[1]); w.y = pk2(o[2], o[3]);
;                     *(u32x2*)(hb + (size_t)r * D + 4 * lane + 256 * j) = w;
;                 }
.LBB0_139:
	s_or_b64 exec, exec, s[10:11]
	v_mov_b32_e32 v82, v77
	v_mov_b32_e32 v83, v73
	v_mov_b32_e32 v80, v76
	v_mov_b32_e32 v81, v72
	v_pk_mul_f32 v[82:83], v[82:83], v[82:83]
	v_mov_b32_e32 v84, v69
	v_pk_fma_f32 v[80:81], v[80:81], v[80:81], v[82:83]
	v_mov_b32_e32 v82, v78
	v_mov_b32_e32 v83, v74
	v_pk_fma_f32 v[80:81], v[82:83], v[82:83], v[80:81]
	v_mov_b32_e32 v82, v79
	v_mov_b32_e32 v83, v75
	v_mov_b32_e32 v85, v65
	v_pk_fma_f32 v[80:81], v[82:83], v[82:83], v[80:81]
	v_mov_b32_e32 v82, v68
	v_mov_b32_e32 v83, v64
	v_pk_mul_f32 v[84:85], v[84:85], v[84:85]
	v_add_f32_e32 v80, v80, v81
	v_pk_fma_f32 v[82:83], v[82:83], v[82:83], v[84:85]
	v_mov_b32_e32 v84, v70
	v_mov_b32_e32 v85, v66
	v_pk_fma_f32 v[82:83], v[84:85], v[84:85], v[82:83]
	v_mov_b32_e32 v84, v71
	v_mov_b32_e32 v85, v67
	v_pk_fma_f32 v[82:83], v[84:85], v[84:85], v[82:83]
	s_nop 0
	v_add_f32_e32 v80, v80, v82
	v_add_f32_e32 v80, v80, v83
	v_mov_b32_e32 v81, v80
	s_nop 1
	v_permlane32_swap_b32_e32 v80, v81
	v_add_f32_e32 v80, v80, v81
	v_mov_b32_e32 v81, v80
	s_nop 1
	v_permlane16_swap_b32_e32 v80, v81
	v_add_f32_e32 v80, v80, v81
	s_nop 1
	v_add_f32_dpp v80, v80, v80 row_ror:8 row_mask:0xf bank_mask:0xf
	s_nop 1
	v_add_f32_dpp v80, v80, v80 row_ror:4 row_mask:0xf bank_mask:0xf
	s_nop 1
	v_add_f32_dpp v80, v80, v80 quad_perm:[2,3,0,1] row_mask:0xf bank_mask:0xf
	s_nop 1
	v_add_f32_dpp v80, v80, v80 quad_perm:[1,0,3,2] row_mask:0xf bank_mask:0xf
	v_fmamk_f32 v80, v80, 0x3a800000, v123
	v_mul_f32_e32 v81, 0x4b800000, v80
	v_cmp_gt_f32_e64 s[4:5], s41, v80
	s_nop 1
	v_cndmask_b32_e64 v80, v80, v81, s[4:5]
	v_rsq_f32_e32 v82, v80
	v_lshl_add_u64 v[80:81], v[112:113], 0, v[108:109]
	v_mul_f32_e32 v83, 0x45800000, v82
	v_cndmask_b32_e64 v82, v82, v83, s[4:5]
	v_pk_mul_f32 v[76:77], v[76:77], v[82:83] op_sel_hi:[1,0]
	v_pk_mul_f32 v[78:79], v[78:79], v[82:83] op_sel_hi:[1,0]
	v_pk_fma_f32 v[76:77], v[28:29], v[76:77], v[12:13]
	v_pk_fma_f32 v[78:79], v[30:31], v[78:79], v[14:15]
	v_cvt_pk_bf16_f32 v76, v76, v77
	v_pk_mul_f32 v[72:73], v[72:73], v[82:83] op_sel_hi:[1,0]
	v_cvt_pk_bf16_f32 v77, v78, v79
	v_add_co_u32_e64 v78, s[4:5], s42, v80
	v_pk_mul_f32 v[68:69], v[68:69], v[82:83] op_sel_hi:[1,0]
	v_pk_mul_f32 v[64:65], v[64:65], v[82:83] op_sel_hi:[1,0]
	v_addc_co_u32_e64 v79, s[4:5], 0, v81, s[4:5]
	v_pk_mul_f32 v[74:75], v[74:75], v[82:83] op_sel_hi:[1,0]
	s_waitcnt vmcnt(2)
	v_pk_fma_f32 v[72:73], v[32:33], v[72:73], v[20:21]
	v_pk_mul_f32 v[70:71], v[70:71], v[82:83] op_sel_hi:[1,0]
	s_waitcnt vmcnt(1)
	v_pk_fma_f32 v[68:69], v[36:37], v[68:69], v[24:25]
	v_pk_mul_f32 v[66:67], v[66:67], v[82:83] op_sel_hi:[1,0]
	s_waitcnt vmcnt(0)
	v_pk_fma_f32 v[64:65], v[44:45], v[64:65], v[40:41]
	global_store_dwordx2 v[78:79], v[76:77], off
	v_pk_fma_f32 v[74:75], v[34:35], v[74:75], v[22:23]
	v_cvt_pk_bf16_f32 v72, v72, v73
	v_pk_fma_f32 v[70:71], v[38:39], v[70:71], v[26:27]
	v_cvt_pk_bf16_f32 v73, v74, v75
	global_store_dwordx2 v[78:79], v[72:73], off offset:512
	v_cvt_pk_bf16_f32 v68, v68, v69
	v_cvt_pk_bf16_f32 v69, v70, v71
	global_store_dwordx2 v[78:79], v[68:69], off offset:1024
	v_pk_fma_f32 v[66:67], v[46:47], v[66:67], v[42:43]
	v_cvt_pk_bf16_f32 v64, v64, v65
	s_nop 0
	v_cvt_pk_bf16_f32 v65, v66, v67
	global_store_dwordx2 v[78:79], v[64:65], off offset:1536
	s_or_b64 exec, exec, s[8:9]
	s_and_saveexec_b64 s[8:9], s[6:7]
	s_cbranch_execz .LBB0_136

; __device__ __forceinline__ unsigned pk2(float lo, float hi) { unsigned r; asm("v_cvt_pk_bf16_f32 %0, %1, %2" : "=v"(r) : "v"(lo), "v"(hi)); return r; }
; __device__ __forceinline__ float row_rstd(const f32x4 (&v)[4]) {
;     float ss = 0.f;
; #pragma unroll
;     for (int j = 0; j < 4; ++j) ss += v[j][0] * v[j][0] + v[j][1] * v[j][1] + v[j][2] * v[j][2] + v[j][3] * v[j][3];
;     return rsqrtf(wave_sum(ss) * (1.0f / D) + EPS);
; __device__ __forceinline__ void phase1(PP p, int wv) {
;     ...
;                 const float rstd = row_rstd(v[q]);
; #pragma unroll
;                 for (int j = 0; j < 4; ++j) {
;                     const f32x4 o = v[q][j] * rstd * gsc[j] + gsh[j];
;                     u32x2 w; w.x = pk2(o[0], o[1]); w.y = pk2(o[2], o[3]);
;                     *(u32x2*)(hb + (size_t)r * D + 4 * lane + 256 * j) = w;
;                 }
.LBB0_142:
	s_or_b64 exec, exec, s[6:7]
	v_mov_b32_e32 v68, v61
	v_mov_b32_e32 v69, v57
	v_mov_b32_e32 v66, v60
	v_mov_b32_e32 v67, v56
	v_pk_mul_f32 v[68:69], v[68:69], v[68:69]
	v_mov_b32_e32 v70, v53
	v_pk_fma_f32 v[66:67], v[66:67], v[66:67], v[68:69]
	v_mov_b32_e32 v68, v62
	v_mov_b32_e32 v69, v58
	v_pk_fma_f32 v[66:67], v[68:69], v[68:69], v[66:67]
	v_mov_b32_e32 v68, v63
	v_mov_b32_e32 v69, v59
	v_mov_b32_e32 v71, v49
	v_pk_fma_f32 v[66:67], v[68:69], v[68:69], v[66:67]
	v_mov_b32_e32 v68, v52
	v_mov_b32_e32 v69, v48
	v_pk_mul_f32 v[70:71], v[70:71], v[70:71]
	v_add_f32_e32 v65, v66, v67
	v_pk_fma_f32 v[68:69], v[68:69], v[68:69], v[70:71]
	v_mov_b32_e32 v70, v54
	v_mov_b32_e32 v71, v50
	v_pk_fma_f32 v[68:69], v[70:71], v[70:71], v[68:69]
	v_mov_b32_e32 v70, v55
	v_mov_b32_e32 v71, v51
	v_pk_fma_f32 v[68:69], v[70:71], v[70:71], v[68:69]
	s_nop 0
	v_add_f32_e32 v65, v65, v68
	v_add_f32_e32 v65, v65, v69
	v_mov_b32_e32 v66, v65
	s_nop 1
	v_permlane32_swap_b32_e32 v65, v66
	v_add_f32_e32 v65, v65, v66
	v_mov_b32_e32 v66, v65
	s_nop 1
	v_permlane16_swap_b32_e32 v65, v66
	v_add_f32_e32 v65, v65, v66
	s_nop 1
	v_add_f32_dpp v65, v65, v65 row_ror:8 row_mask:0xf bank_mask:0xf
	s_nop 1
	v_add_f32_dpp v65, v65, v65 row_ror:4 row_mask:0xf bank_mask:0xf
	s_nop 1
	v_add_f32_dpp v65, v65, v65 quad_perm:[2,3,0,1] row_mask:0xf bank_mask:0xf
	s_nop 1
	v_add_f32_dpp v65, v65, v65 quad_perm:[1,0,3,2] row_mask:0xf bank_mask:0xf
	v_fmamk_f32 v65, v65, 0x3a800000, v123
	v_mul_f32_e32 v66, 0x4b800000, v65
	v_cmp_gt_f32_e64 s[4:5], s41, v65
	s_nop 1
	v_cndmask_b32_e64 v65, v65, v66, s[4:5]
	v_rsq_f32_e32 v66, v65
	v_ashrrev_i32_e32 v65, 31, v64
	v_lshlrev_b64 v[64:65], 11, v[64:65]
	v_lshl_add_u64 v[64:65], v[100:101], 0, v[64:65]
	v_mul_f32_e32 v67, 0x45800000, v66
	v_cndmask_b32_e64 v66, v66, v67, s[4:5]
	v_pk_mul_f32 v[60:61], v[60:61], v[66:67] op_sel_hi:[1,0]
	v_pk_mul_f32 v[56:57], v[56:57], v[66:67] op_sel_hi:[1,0]
	v_pk_mul_f32 v[52:53], v[52:53], v[66:67] op_sel_hi:[1,0]
	v_pk_mul_f32 v[48:49], v[48:49], v[66:67] op_sel_hi:[1,0]
	v_pk_mul_f32 v[62:63], v[62:63], v[66:67] op_sel_hi:[1,0]
	v_pk_fma_f32 v[60:61], v[28:29], v[60:61], v[12:13]
	v_pk_mul_f32 v[58:59], v[58:59], v[66:67] op_sel_hi:[1,0]
	s_waitcnt vmcnt(2)
	v_pk_fma_f32 v[56:57], v[32:33], v[56:57], v[20:21]
	v_pk_mul_f32 v[54:55], v[54:55], v[66:67] op_sel_hi:[1,0]
	s_waitcnt vmcnt(1)
	v_pk_fma_f32 v[52:53], v[36:37], v[52:53], v[24:25]
	v_pk_mul_f32 v[50:51], v[50:51], v[66:67] op_sel_hi:[1,0]
	s_waitcnt vmcnt(0)
	v_pk_fma_f32 v[48:49], v[44:45], v[48:49], v[40:41]
	v_pk_fma_f32 v[62:63], v[30:31], v[62:63], v[14:15]
	v_cvt_pk_bf16_f32 v60, v60, v61
	v_pk_fma_f32 v[58:59], v[34:35], v[58:59], v[22:23]
	v_cvt_pk_bf16_f32 v61, v62, v63
	global_store_dwordx2 v[64:65], v[60:61], off
	v_cvt_pk_bf16_f32 v56, v56, v57
	v_cvt_pk_bf16_f32 v57, v58, v59
	global_store_dwordx2 v[64:65], v[56:57], off offset:512
	v_pk_fma_f32 v[54:55], v[38:39], v[54:55], v[26:27]
	v_cvt_pk_bf16_f32 v52, v52, v53
	v_pk_fma_f32 v[50:51], v[46:47], v[50:51], v[42:43]
	v_cvt_pk_bf16_f32 v53, v54, v55
	global_store_dwordx2 v[64:65], v[52:53], off offset:1024
	v_cvt_pk_bf16_f32 v48, v48, v49
	v_cvt_pk_bf16_f32 v49, v50, v51
	global_store_dwordx2 v[64:65], v[48:49], off offset:1536
	s_or_b64 exec, exec, s[8:9]
	s_and_saveexec_b64 s[4:5], vcc
	s_cbranch_execz .LBB0_131
